# + XCD leader no longer bumps the per-XCD release word (nobody polls it since the direct release-word polling)
# speedup vs baseline: 1.0083x; 1.0032x over previous
; __device__ __forceinline__ unsigned xb_ld(unsigned* p)              { return __hip_atomic_load(p, __ATOMIC_RELAXED, __HIP_MEMORY_SCOPE_AGENT); }
; __device__ __forceinline__ unsigned xb_add(unsigned* p, unsigned v) { return __hip_atomic_fetch_add(p, v, __ATOMIC_RELAXED, __HIP_MEMORY_SCOPE_AGENT); }
; #define XB_SPIN(cond, bar) do { unsigned _sp = 0; while (cond) { __builtin_amdgcn_s_sleep(1); \
;     if ((++_sp & 255u) == 0u) { if (xb_ld(&(bar)[XB_TMO])) break; if (_sp > XB_SPIN_CAP) { atomicAdd(&(bar)[XB_TMO], 1u); break; } } } } while (0)
; __device__ __forceinline__ void xcd_barrier(const XcdBarrier& b) {
;     ...
;             else XB_SPIN(xb_ld(&bar[XB_TOPGEN]) == tg, bar);
;             __builtin_amdgcn_fence(__ATOMIC_ACQUIRE, "agent");
;             xb_add(&bar[XB_XGEN(b.x)], 1u);
;             asm volatile("s_waitcnt vmcnt(0)" ::: "memory");
.LBB0_112:
	s_or_b64 exec, exec, s[8:9]
	s_mov_b64 s[8:9], exec
	v_mbcnt_lo_u32_b32 v0, s8, 0
	v_mbcnt_hi_u32_b32 v0, s9, v0
	v_cmp_eq_u32_e32 vcc, 0, v0
	s_waitcnt vmcnt(0)
	buffer_inv sc1
	s_and_saveexec_b64 s[10:11], vcc
	s_cbranch_execz .LBB0_114
	s_bcnt1_i32_b64 s3, s[8:9]
	v_mov_b32_e32 v0, 0x2000
	v_mov_b32_e32 v1, s3
.LBB0_114:
	s_or_b64 exec, exec, s[10:11]
	s_waitcnt vmcnt(0)

; __device__ __forceinline__ unsigned xb_ld(unsigned* p)              { return __hip_atomic_load(p, __ATOMIC_RELAXED, __HIP_MEMORY_SCOPE_AGENT); }
; __device__ __forceinline__ unsigned xb_add(unsigned* p, unsigned v) { return __hip_atomic_fetch_add(p, v, __ATOMIC_RELAXED, __HIP_MEMORY_SCOPE_AGENT); }
; #define XB_SPIN(cond, bar) do { unsigned _sp = 0; while (cond) { __builtin_amdgcn_s_sleep(1); \
;     if ((++_sp & 255u) == 0u) { if (xb_ld(&(bar)[XB_TMO])) break; if (_sp > XB_SPIN_CAP) { atomicAdd(&(bar)[XB_TMO], 1u); break; } } } } while (0)
; __device__ __forceinline__ void xcd_barrier(const XcdBarrier& b) {
;     ...
;             else XB_SPIN(xb_ld(&bar[XB_TOPGEN]) == tg, bar);
;             __builtin_amdgcn_fence(__ATOMIC_ACQUIRE, "agent");
;             xb_add(&bar[XB_XGEN(b.x)], 1u);
;             asm volatile("s_waitcnt vmcnt(0)" ::: "memory");
.LBB0_180:
	s_or_b64 exec, exec, s[12:13]
	s_mov_b64 s[12:13], exec
	v_mbcnt_lo_u32_b32 v0, s12, 0
	v_mbcnt_hi_u32_b32 v0, s13, v0
	v_cmp_eq_u32_e32 vcc, 0, v0
	s_waitcnt vmcnt(0)
	buffer_inv sc1
	s_and_saveexec_b64 s[14:15], vcc
	s_cbranch_execz .LBB0_182
	s_bcnt1_i32_b64 s3, s[12:13]
	v_mov_b32_e32 v0, 0x2000
	v_mov_b32_e32 v1, s3
.LBB0_182:
	s_or_b64 exec, exec, s[14:15]
	s_waitcnt vmcnt(0)

; __device__ __forceinline__ unsigned xb_ld(unsigned* p)              { return __hip_atomic_load(p, __ATOMIC_RELAXED, __HIP_MEMORY_SCOPE_AGENT); }
; __device__ __forceinline__ unsigned xb_add(unsigned* p, unsigned v) { return __hip_atomic_fetch_add(p, v, __ATOMIC_RELAXED, __HIP_MEMORY_SCOPE_AGENT); }
; #define XB_SPIN(cond, bar) do { unsigned _sp = 0; while (cond) { __builtin_amdgcn_s_sleep(1); \
;     if ((++_sp & 255u) == 0u) { if (xb_ld(&(bar)[XB_TMO])) break; if (_sp > XB_SPIN_CAP) { atomicAdd(&(bar)[XB_TMO], 1u); break; } } } } while (0)
; __device__ __forceinline__ void xcd_barrier(const XcdBarrier& b) {
;     ...
;             else XB_SPIN(xb_ld(&bar[XB_TOPGEN]) == tg, bar);
;             __builtin_amdgcn_fence(__ATOMIC_ACQUIRE, "agent");
;             xb_add(&bar[XB_XGEN(b.x)], 1u);
;             asm volatile("s_waitcnt vmcnt(0)" ::: "memory");
.LBB0_258:
	s_or_b64 exec, exec, s[10:11]
	s_mov_b64 s[10:11], exec
	v_mbcnt_lo_u32_b32 v0, s10, 0
	v_mbcnt_hi_u32_b32 v0, s11, v0
	v_cmp_eq_u32_e32 vcc, 0, v0
	s_waitcnt vmcnt(0)
	buffer_inv sc1
	s_and_saveexec_b64 s[12:13], vcc
	s_cbranch_execz .LBB0_260
	s_bcnt1_i32_b64 s3, s[10:11]
	v_mov_b32_e32 v0, 0x2000
	v_mov_b32_e32 v1, s3
.LBB0_260:
	s_or_b64 exec, exec, s[12:13]
	s_waitcnt vmcnt(0)

; __device__ __forceinline__ unsigned xb_ld(unsigned* p)              { return __hip_atomic_load(p, __ATOMIC_RELAXED, __HIP_MEMORY_SCOPE_AGENT); }
; __device__ __forceinline__ unsigned xb_add(unsigned* p, unsigned v) { return __hip_atomic_fetch_add(p, v, __ATOMIC_RELAXED, __HIP_MEMORY_SCOPE_AGENT); }
; #define XB_SPIN(cond, bar) do { unsigned _sp = 0; while (cond) { __builtin_amdgcn_s_sleep(1); \
;     if ((++_sp & 255u) == 0u) { if (xb_ld(&(bar)[XB_TMO])) break; if (_sp > XB_SPIN_CAP) { atomicAdd(&(bar)[XB_TMO], 1u); break; } } } } while (0)
; __device__ __forceinline__ void xcd_barrier(const XcdBarrier& b) {
;     ...
;             else XB_SPIN(xb_ld(&bar[XB_TOPGEN]) == tg, bar);
;             __builtin_amdgcn_fence(__ATOMIC_ACQUIRE, "agent");
;             xb_add(&bar[XB_XGEN(b.x)], 1u);
;             asm volatile("s_waitcnt vmcnt(0)" ::: "memory");
.LBB0_362:
	s_or_b64 exec, exec, s[10:11]
	s_mov_b64 s[10:11], exec
	v_mbcnt_lo_u32_b32 v0, s10, 0
	v_mbcnt_hi_u32_b32 v0, s11, v0
	v_cmp_eq_u32_e32 vcc, 0, v0
	s_waitcnt vmcnt(0)
	buffer_inv sc1
	s_and_saveexec_b64 s[12:13], vcc
	s_cbranch_execz .LBB0_364
	s_bcnt1_i32_b64 s3, s[10:11]
	v_mov_b32_e32 v0, 0x2000
	v_mov_b32_e32 v1, s3
.LBB0_364:
	s_or_b64 exec, exec, s[12:13]
	s_waitcnt vmcnt(0)

; __device__ __forceinline__ unsigned xb_ld(unsigned* p)              { return __hip_atomic_load(p, __ATOMIC_RELAXED, __HIP_MEMORY_SCOPE_AGENT); }
; __device__ __forceinline__ unsigned xb_add(unsigned* p, unsigned v) { return __hip_atomic_fetch_add(p, v, __ATOMIC_RELAXED, __HIP_MEMORY_SCOPE_AGENT); }
; #define XB_SPIN(cond, bar) do { unsigned _sp = 0; while (cond) { __builtin_amdgcn_s_sleep(1); \
;     if ((++_sp & 255u) == 0u) { if (xb_ld(&(bar)[XB_TMO])) break; if (_sp > XB_SPIN_CAP) { atomicAdd(&(bar)[XB_TMO], 1u); break; } } } } while (0)
; __device__ __forceinline__ void xcd_barrier(const XcdBarrier& b) {
;     ...
;             else XB_SPIN(xb_ld(&bar[XB_TOPGEN]) == tg, bar);
;             __builtin_amdgcn_fence(__ATOMIC_ACQUIRE, "agent");
;             xb_add(&bar[XB_XGEN(b.x)], 1u);
;             asm volatile("s_waitcnt vmcnt(0)" ::: "memory");
.LBB0_530:
	s_or_b64 exec, exec, s[8:9]
	s_mov_b64 s[8:9], exec
	v_mbcnt_lo_u32_b32 v0, s8, 0
	v_mbcnt_hi_u32_b32 v0, s9, v0
	v_cmp_eq_u32_e32 vcc, 0, v0
	s_waitcnt vmcnt(0)
	buffer_inv sc1
	s_and_saveexec_b64 s[10:11], vcc
	s_cbranch_execz .LBB0_532
	s_bcnt1_i32_b64 s3, s[8:9]
	v_mov_b32_e32 v0, 0x2000
	v_mov_b32_e32 v1, s3
.LBB0_532:
	s_or_b64 exec, exec, s[10:11]
	s_waitcnt vmcnt(0)

; __device__ __forceinline__ unsigned xb_ld(unsigned* p)              { return __hip_atomic_load(p, __ATOMIC_RELAXED, __HIP_MEMORY_SCOPE_AGENT); }
; __device__ __forceinline__ unsigned xb_add(unsigned* p, unsigned v) { return __hip_atomic_fetch_add(p, v, __ATOMIC_RELAXED, __HIP_MEMORY_SCOPE_AGENT); }
; #define XB_SPIN(cond, bar) do { unsigned _sp = 0; while (cond) { __builtin_amdgcn_s_sleep(1); \
;     if ((++_sp & 255u) == 0u) { if (xb_ld(&(bar)[XB_TMO])) break; if (_sp > XB_SPIN_CAP) { atomicAdd(&(bar)[XB_TMO], 1u); break; } } } } while (0)
; __device__ __forceinline__ void xcd_barrier(const XcdBarrier& b) {
;     ...
;             else XB_SPIN(xb_ld(&bar[XB_TOPGEN]) == tg, bar);
;             __builtin_amdgcn_fence(__ATOMIC_ACQUIRE, "agent");
;             xb_add(&bar[XB_XGEN(b.x)], 1u);
;             asm volatile("s_waitcnt vmcnt(0)" ::: "memory");
.LBB0_629:
	s_or_b64 exec, exec, s[8:9]
	s_mov_b64 s[8:9], exec
	v_mbcnt_lo_u32_b32 v0, s8, 0
	v_mbcnt_hi_u32_b32 v0, s9, v0
	v_cmp_eq_u32_e32 vcc, 0, v0
	s_waitcnt vmcnt(0)
	buffer_inv sc1
	s_and_saveexec_b64 s[10:11], vcc
	s_cbranch_execz .LBB0_631
	s_bcnt1_i32_b64 s8, s[8:9]
	v_mov_b32_e32 v0, 0x2000
	v_mov_b32_e32 v1, s8
.LBB0_631:
	s_or_b64 exec, exec, s[10:11]
	s_waitcnt vmcnt(0)

; __device__ __forceinline__ unsigned xb_ld(unsigned* p)              { return __hip_atomic_load(p, __ATOMIC_RELAXED, __HIP_MEMORY_SCOPE_AGENT); }
; __device__ __forceinline__ unsigned xb_add(unsigned* p, unsigned v) { return __hip_atomic_fetch_add(p, v, __ATOMIC_RELAXED, __HIP_MEMORY_SCOPE_AGENT); }
; #define XB_SPIN(cond, bar) do { unsigned _sp = 0; while (cond) { __builtin_amdgcn_s_sleep(1); \
;     if ((++_sp & 255u) == 0u) { if (xb_ld(&(bar)[XB_TMO])) break; if (_sp > XB_SPIN_CAP) { atomicAdd(&(bar)[XB_TMO], 1u); break; } } } } while (0)
; __device__ __forceinline__ void xcd_barrier(const XcdBarrier& b) {
;     ...
;             else XB_SPIN(xb_ld(&bar[XB_TOPGEN]) == tg, bar);
;             __builtin_amdgcn_fence(__ATOMIC_ACQUIRE, "agent");
;             xb_add(&bar[XB_XGEN(b.x)], 1u);
;             asm volatile("s_waitcnt vmcnt(0)" ::: "memory");
.LBB0_769:
	s_or_b64 exec, exec, s[10:11]
	s_mov_b64 s[10:11], exec
	v_mbcnt_lo_u32_b32 v0, s10, 0
	v_mbcnt_hi_u32_b32 v0, s11, v0
	v_cmp_eq_u32_e32 vcc, 0, v0
	s_waitcnt vmcnt(0)
	buffer_inv sc1
	s_and_saveexec_b64 s[12:13], vcc
	s_cbranch_execz .LBB0_771
	s_bcnt1_i32_b64 s3, s[10:11]
	v_mov_b32_e32 v0, 0x2000
	v_mov_b32_e32 v1, s3
.LBB0_771:
	s_or_b64 exec, exec, s[12:13]
	s_waitcnt vmcnt(0)

; __device__ __forceinline__ unsigned xb_ld(unsigned* p)              { return __hip_atomic_load(p, __ATOMIC_RELAXED, __HIP_MEMORY_SCOPE_AGENT); }
; __device__ __forceinline__ unsigned xb_add(unsigned* p, unsigned v) { return __hip_atomic_fetch_add(p, v, __ATOMIC_RELAXED, __HIP_MEMORY_SCOPE_AGENT); }
; #define XB_SPIN(cond, bar) do { unsigned _sp = 0; while (cond) { __builtin_amdgcn_s_sleep(1); \
;     if ((++_sp & 255u) == 0u) { if (xb_ld(&(bar)[XB_TMO])) break; if (_sp > XB_SPIN_CAP) { atomicAdd(&(bar)[XB_TMO], 1u); break; } } } } while (0)
; __device__ __forceinline__ void xcd_barrier(const XcdBarrier& b) {
;     ...
;             else XB_SPIN(xb_ld(&bar[XB_TOPGEN]) == tg, bar);
;             __builtin_amdgcn_fence(__ATOMIC_ACQUIRE, "agent");
;             xb_add(&bar[XB_XGEN(b.x)], 1u);
;             asm volatile("s_waitcnt vmcnt(0)" ::: "memory");
.LBB0_881:
	s_or_b64 exec, exec, s[12:13]
	s_mov_b64 s[12:13], exec
	v_mbcnt_lo_u32_b32 v0, s12, 0
	v_mbcnt_hi_u32_b32 v0, s13, v0
	v_cmp_eq_u32_e32 vcc, 0, v0
	s_waitcnt vmcnt(0)
	buffer_inv sc1
	s_and_saveexec_b64 s[14:15], vcc
	s_cbranch_execz .LBB0_883
	s_bcnt1_i32_b64 s3, s[12:13]
	v_mov_b32_e32 v0, 0x2000
	v_mov_b32_e32 v1, s3
.LBB0_883:
	s_or_b64 exec, exec, s[14:15]
	s_waitcnt vmcnt(0)

; __device__ __forceinline__ unsigned xb_ld(unsigned* p)              { return __hip_atomic_load(p, __ATOMIC_RELAXED, __HIP_MEMORY_SCOPE_AGENT); }
; __device__ __forceinline__ unsigned xb_add(unsigned* p, unsigned v) { return __hip_atomic_fetch_add(p, v, __ATOMIC_RELAXED, __HIP_MEMORY_SCOPE_AGENT); }
; #define XB_SPIN(cond, bar) do { unsigned _sp = 0; while (cond) { __builtin_amdgcn_s_sleep(1); \
;     if ((++_sp & 255u) == 0u) { if (xb_ld(&(bar)[XB_TMO])) break; if (_sp > XB_SPIN_CAP) { atomicAdd(&(bar)[XB_TMO], 1u); break; } } } } while (0)
; __device__ __forceinline__ void xcd_barrier(const XcdBarrier& b) {
;     ...
;             else XB_SPIN(xb_ld(&bar[XB_TOPGEN]) == tg, bar);
;             __builtin_amdgcn_fence(__ATOMIC_ACQUIRE, "agent");
;             xb_add(&bar[XB_XGEN(b.x)], 1u);
;             asm volatile("s_waitcnt vmcnt(0)" ::: "memory");
.LBB0_965:
	s_or_b64 exec, exec, s[10:11]
	s_mov_b64 s[10:11], exec
	v_mbcnt_lo_u32_b32 v0, s10, 0
	v_mbcnt_hi_u32_b32 v0, s11, v0
	v_cmp_eq_u32_e32 vcc, 0, v0
	s_waitcnt vmcnt(0)
	buffer_inv sc1
	s_and_saveexec_b64 s[12:13], vcc
	s_cbranch_execz .LBB0_967
	s_bcnt1_i32_b64 s3, s[10:11]
	v_mov_b32_e32 v0, 0x2000
	v_mov_b32_e32 v1, s3
.LBB0_967:
	s_or_b64 exec, exec, s[12:13]
	s_waitcnt vmcnt(0)
